# c1 plus 64-byte alignment of the seven GEMM K-loop heads (code placement)
# baseline (speedup 1.0000x reference)
; __device__ __forceinline__ const char* b_base(const Gemm& g, const Unit& u) { return (const char*)g.Bt + (size_t)u.pn * 2 * (g.K >> 6) * BLK; }
; template <class Epi, bool ALIGN_EPI = true, bool SP2 = true>
; __device__ __forceinline__ void gemm_phase(LAS unsigned char* lds, const Gemm g, const StaticOrder& S, const Epi& E, unsigned long long& tacc, const int tmode) {
;     ...
;         const bool has_next = S.next(ui + 1, nxt);
;         const char* nA = has_next ? a_base(g, nxt) : cA; const char* nB = has_next ? b_base(g, nxt) : cB;
;     ...
; #pragma unroll
;         for (int a = 0; a < 2; ++a)
; #pragma unroll
;             for (int b = 0; b < 2; ++b)
; #pragma unroll
;                 for (int m = 0; m < 4; ++m)
; #pragma unroll
;                     for (int n = 0; n < 2; ++n) acc[a][b][m][n] = (f32x4){0.f, 0.f, 0.f, 0.f};
.LBB0_132:
	s_ashr_i32 s25, s24, 31
	s_lshl_b64 s[0:1], s[24:25], 20
	v_readlane_b32 s26, v255, 9
	v_readlane_b32 s27, v255, 10
	s_add_u32 s26, s26, s0
	s_addc_u32 s27, s27, s1
	s_and_b64 s[0:1], s[36:37], exec
	s_cselect_b32 s25, s27, s23
	s_cselect_b32 s50, s26, s22
	s_ashr_i32 s21, s20, 31
	s_lshl_b64 s[0:1], s[20:21], 20
	v_readlane_b32 s21, v254, 6
	s_add_u32 s28, s21, s0
	v_readlane_b32 s0, v254, 7
	s_addc_u32 s29, s0, s1
	s_and_b64 s[0:1], s[36:37], exec
	s_cselect_b32 s21, s29, s31
	s_cselect_b32 s51, s28, s30
	s_add_u32 s22, s22, 0x84000
	s_addc_u32 s23, s23, 0
	s_add_u32 s54, s30, 0x8000
	v_mov_b32_e32 v2, 0
	s_addc_u32 s55, s31, 0
	s_mov_b32 s56, -2
	v_mov_b32_e32 v3, v2
	v_mov_b32_e32 v4, v2
	v_mov_b32_e32 v5, v2
	v_mov_b32_e32 v6, v2
	v_mov_b32_e32 v7, v2
	v_mov_b32_e32 v8, v2
	v_mov_b32_e32 v9, v2
	v_mov_b32_e32 v18, v2
	v_mov_b32_e32 v19, v2
	v_mov_b32_e32 v20, v2
	v_mov_b32_e32 v21, v2
	v_mov_b32_e32 v22, v2
	v_mov_b32_e32 v23, v2
	v_mov_b32_e32 v24, v2
	v_mov_b32_e32 v25, v2
	v_mov_b32_e32 v34, v2
	v_mov_b32_e32 v35, v2
	v_mov_b32_e32 v36, v2
	v_mov_b32_e32 v37, v2
	v_mov_b32_e32 v38, v2
	v_mov_b32_e32 v39, v2
	v_mov_b32_e32 v40, v2
	v_mov_b32_e32 v41, v2
	v_mov_b32_e32 v50, v2
	v_mov_b32_e32 v51, v2
	v_mov_b32_e32 v52, v2
	v_mov_b32_e32 v53, v2
	v_mov_b32_e32 v54, v2
	v_mov_b32_e32 v55, v2
	v_mov_b32_e32 v56, v2
	v_mov_b32_e32 v57, v2
	v_mov_b32_e32 v10, v2
	v_mov_b32_e32 v11, v2
	v_mov_b32_e32 v12, v2
	v_mov_b32_e32 v13, v2
	v_mov_b32_e32 v14, v2
	v_mov_b32_e32 v15, v2
	v_mov_b32_e32 v16, v2
	v_mov_b32_e32 v17, v2
	v_mov_b32_e32 v26, v2
	v_mov_b32_e32 v27, v2
	v_mov_b32_e32 v28, v2
	v_mov_b32_e32 v29, v2
	v_mov_b32_e32 v30, v2
	v_mov_b32_e32 v31, v2
	v_mov_b32_e32 v32, v2
	v_mov_b32_e32 v33, v2
	v_mov_b32_e32 v42, v2
	v_mov_b32_e32 v43, v2
	v_mov_b32_e32 v44, v2
	v_mov_b32_e32 v45, v2
	v_mov_b32_e32 v46, v2
	v_mov_b32_e32 v47, v2
	v_mov_b32_e32 v48, v2
	v_mov_b32_e32 v49, v2
	v_mov_b32_e32 v58, v2
	v_mov_b32_e32 v59, v2
	v_mov_b32_e32 v60, v2
	v_mov_b32_e32 v61, v2
	v_mov_b32_e32 v62, v2
	v_mov_b32_e32 v63, v2
	v_mov_b32_e32 v64, v2
	v_mov_b32_e32 v65, v2
	v_mov_b32_e32 v66, v2
	v_mov_b32_e32 v67, v2
	v_mov_b32_e32 v68, v2
	v_mov_b32_e32 v69, v2
	v_mov_b32_e32 v70, v2
	v_mov_b32_e32 v71, v2
	v_mov_b32_e32 v72, v2
	v_mov_b32_e32 v73, v2
	v_mov_b32_e32 v82, v2
	v_mov_b32_e32 v83, v2
	v_mov_b32_e32 v84, v2
	v_mov_b32_e32 v85, v2
	v_mov_b32_e32 v86, v2
	v_mov_b32_e32 v87, v2
	v_mov_b32_e32 v88, v2
	v_mov_b32_e32 v89, v2
	v_mov_b32_e32 v98, v2
	v_mov_b32_e32 v99, v2
	v_mov_b32_e32 v100, v2
	v_mov_b32_e32 v101, v2
	v_mov_b32_e32 v102, v2
	v_mov_b32_e32 v103, v2
	v_mov_b32_e32 v104, v2
	v_mov_b32_e32 v105, v2
	v_mov_b32_e32 v114, v2
	v_mov_b32_e32 v115, v2
	v_mov_b32_e32 v116, v2
	v_mov_b32_e32 v117, v2
	v_mov_b32_e32 v118, v2
	v_mov_b32_e32 v119, v2
	v_mov_b32_e32 v120, v2
	v_mov_b32_e32 v121, v2
	v_mov_b32_e32 v74, v2
	v_mov_b32_e32 v75, v2
	v_mov_b32_e32 v76, v2
	v_mov_b32_e32 v77, v2
	v_mov_b32_e32 v78, v2
	v_mov_b32_e32 v79, v2
	v_mov_b32_e32 v80, v2
	v_mov_b32_e32 v81, v2
	v_mov_b32_e32 v90, v2
	v_mov_b32_e32 v91, v2
	v_mov_b32_e32 v92, v2
	v_mov_b32_e32 v93, v2
	v_mov_b32_e32 v94, v2
	v_mov_b32_e32 v95, v2
	v_mov_b32_e32 v96, v2
	v_mov_b32_e32 v97, v2
	v_mov_b32_e32 v106, v2
	v_mov_b32_e32 v107, v2
	v_mov_b32_e32 v108, v2
	v_mov_b32_e32 v109, v2
	v_mov_b32_e32 v110, v2
	v_mov_b32_e32 v111, v2
	v_mov_b32_e32 v112, v2
	v_mov_b32_e32 v113, v2
	v_mov_b32_e32 v122, v2
	v_mov_b32_e32 v123, v2
	v_mov_b32_e32 v124, v2
	v_mov_b32_e32 v125, v2
	v_mov_b32_e32 v126, v2
	v_mov_b32_e32 v127, v2
	v_mov_b32_e32 v128, v2
	v_mov_b32_e32 v129, v2
	.p2align 6

; __device__ __forceinline__ const char* b_base(const Gemm& g, const Unit& u) { return (const char*)g.Bt + (size_t)u.pn * 2 * (g.K >> 6) * BLK; }
; template <class Epi, bool ALIGN_EPI = true, bool SP2 = true>
; __device__ __forceinline__ void gemm_phase(LAS unsigned char* lds, const Gemm g, const StaticOrder& S, const Epi& E, unsigned long long& tacc, const int tmode) {
;     ...
;         const bool has_next = S.next(ui + 1, nxt);
;         const char* nA = has_next ? a_base(g, nxt) : cA; const char* nB = has_next ? b_base(g, nxt) : cB;
;     ...
; #pragma unroll
;         for (int a = 0; a < 2; ++a)
; #pragma unroll
;             for (int b = 0; b < 2; ++b)
; #pragma unroll
;                 for (int m = 0; m < 4; ++m)
; #pragma unroll
;                     for (int n = 0; n < 2; ++n) acc[a][b][m][n] = (f32x4){0.f, 0.f, 0.f, 0.f};
.LBB0_580:
	s_ashr_i32 s25, s24, 31
	s_lshl_b64 s[0:1], s[24:25], 20
	v_readlane_b32 s26, v255, 9
	v_readlane_b32 s27, v255, 10
	s_add_u32 s26, s26, s0
	s_addc_u32 s27, s27, s1
	s_and_b64 s[0:1], s[36:37], exec
	s_cselect_b32 s25, s27, s23
	s_cselect_b32 s50, s26, s22
	s_ashr_i32 s21, s20, 31
	s_lshl_b64 s[0:1], s[20:21], 20
	v_readlane_b32 s21, v253, 32
	s_add_u32 s28, s21, s0
	v_readlane_b32 s0, v253, 33
	s_addc_u32 s29, s0, s1
	s_and_b64 s[0:1], s[36:37], exec
	s_cselect_b32 s21, s29, s31
	s_cselect_b32 s51, s28, s30
	s_add_u32 s22, s22, 0x84000
	s_addc_u32 s23, s23, 0
	s_add_u32 s54, s30, 0x8000
	v_mov_b32_e32 v2, 0
	s_addc_u32 s55, s31, 0
	s_mov_b32 s56, -2
	v_mov_b32_e32 v3, v2
	v_mov_b32_e32 v4, v2
	v_mov_b32_e32 v5, v2
	v_mov_b32_e32 v6, v2
	v_mov_b32_e32 v7, v2
	v_mov_b32_e32 v8, v2
	v_mov_b32_e32 v9, v2
	v_mov_b32_e32 v10, v2
	v_mov_b32_e32 v11, v2
	v_mov_b32_e32 v12, v2
	v_mov_b32_e32 v13, v2
	v_mov_b32_e32 v14, v2
	v_mov_b32_e32 v15, v2
	v_mov_b32_e32 v16, v2
	v_mov_b32_e32 v17, v2
	v_mov_b32_e32 v18, v2
	v_mov_b32_e32 v19, v2
	v_mov_b32_e32 v20, v2
	v_mov_b32_e32 v21, v2
	v_mov_b32_e32 v22, v2
	v_mov_b32_e32 v23, v2
	v_mov_b32_e32 v24, v2
	v_mov_b32_e32 v25, v2
	v_mov_b32_e32 v26, v2
	v_mov_b32_e32 v27, v2
	v_mov_b32_e32 v28, v2
	v_mov_b32_e32 v29, v2
	v_mov_b32_e32 v30, v2
	v_mov_b32_e32 v31, v2
	v_mov_b32_e32 v32, v2
	v_mov_b32_e32 v33, v2
	v_mov_b32_e32 v66, v2
	v_mov_b32_e32 v67, v2
	v_mov_b32_e32 v68, v2
	v_mov_b32_e32 v69, v2
	v_mov_b32_e32 v70, v2
	v_mov_b32_e32 v71, v2
	v_mov_b32_e32 v72, v2
	v_mov_b32_e32 v73, v2
	v_mov_b32_e32 v74, v2
	v_mov_b32_e32 v75, v2
	v_mov_b32_e32 v76, v2
	v_mov_b32_e32 v77, v2
	v_mov_b32_e32 v78, v2
	v_mov_b32_e32 v79, v2
	v_mov_b32_e32 v80, v2
	v_mov_b32_e32 v81, v2
	v_mov_b32_e32 v82, v2
	v_mov_b32_e32 v83, v2
	v_mov_b32_e32 v84, v2
	v_mov_b32_e32 v85, v2
	v_mov_b32_e32 v86, v2
	v_mov_b32_e32 v87, v2
	v_mov_b32_e32 v88, v2
	v_mov_b32_e32 v89, v2
	v_mov_b32_e32 v90, v2
	v_mov_b32_e32 v91, v2
	v_mov_b32_e32 v92, v2
	v_mov_b32_e32 v93, v2
	v_mov_b32_e32 v94, v2
	v_mov_b32_e32 v95, v2
	v_mov_b32_e32 v96, v2
	v_mov_b32_e32 v97, v2
	v_mov_b32_e32 v34, v2
	v_mov_b32_e32 v35, v2
	v_mov_b32_e32 v36, v2
	v_mov_b32_e32 v37, v2
	v_mov_b32_e32 v38, v2
	v_mov_b32_e32 v39, v2
	v_mov_b32_e32 v40, v2
	v_mov_b32_e32 v41, v2
	v_mov_b32_e32 v42, v2
	v_mov_b32_e32 v43, v2
	v_mov_b32_e32 v44, v2
	v_mov_b32_e32 v45, v2
	v_mov_b32_e32 v46, v2
	v_mov_b32_e32 v47, v2
	v_mov_b32_e32 v48, v2
	v_mov_b32_e32 v49, v2
	v_mov_b32_e32 v50, v2
	v_mov_b32_e32 v51, v2
	v_mov_b32_e32 v52, v2
	v_mov_b32_e32 v53, v2
	v_mov_b32_e32 v54, v2
	v_mov_b32_e32 v55, v2
	v_mov_b32_e32 v56, v2
	v_mov_b32_e32 v57, v2
	v_mov_b32_e32 v58, v2
	v_mov_b32_e32 v59, v2
	v_mov_b32_e32 v60, v2
	v_mov_b32_e32 v61, v2
	v_mov_b32_e32 v62, v2
	v_mov_b32_e32 v63, v2
	v_mov_b32_e32 v64, v2
	v_mov_b32_e32 v65, v2
	v_mov_b32_e32 v98, v2
	v_mov_b32_e32 v99, v2
	v_mov_b32_e32 v100, v2
	v_mov_b32_e32 v101, v2
	v_mov_b32_e32 v102, v2
	v_mov_b32_e32 v103, v2
	v_mov_b32_e32 v104, v2
	v_mov_b32_e32 v105, v2
	v_mov_b32_e32 v106, v2
	v_mov_b32_e32 v107, v2
	v_mov_b32_e32 v108, v2
	v_mov_b32_e32 v109, v2
	v_mov_b32_e32 v110, v2
	v_mov_b32_e32 v111, v2
	v_mov_b32_e32 v112, v2
	v_mov_b32_e32 v113, v2
	v_mov_b32_e32 v114, v2
	v_mov_b32_e32 v115, v2
	v_mov_b32_e32 v116, v2
	v_mov_b32_e32 v117, v2
	v_mov_b32_e32 v118, v2
	v_mov_b32_e32 v119, v2
	v_mov_b32_e32 v120, v2
	v_mov_b32_e32 v121, v2
	v_mov_b32_e32 v122, v2
	v_mov_b32_e32 v123, v2
	v_mov_b32_e32 v124, v2
	v_mov_b32_e32 v125, v2
	v_mov_b32_e32 v126, v2
	v_mov_b32_e32 v127, v2
	v_mov_b32_e32 v128, v2
	v_mov_b32_e32 v129, v2
	v_readlane_b32 s0, v254, 19
	.p2align 6

; __device__ __forceinline__ const char* b_base(const Gemm& g, const Unit& u) { return (const char*)g.Bt + (size_t)u.pn * 2 * (g.K >> 6) * BLK; }
; template <class Epi, bool ALIGN_EPI = true, bool SP2 = true>
; __device__ __forceinline__ void gemm_phase(LAS unsigned char* lds, const Gemm g, const StaticOrder& S, const Epi& E, unsigned long long& tacc, const int tmode) {
;     ...
;         const bool has_next = S.next(ui + 1, nxt);
;         const char* nA = has_next ? a_base(g, nxt) : cA; const char* nB = has_next ? b_base(g, nxt) : cB;
;     ...
; #pragma unroll
;         for (int a = 0; a < 2; ++a)
; #pragma unroll
;             for (int b = 0; b < 2; ++b)
; #pragma unroll
;                 for (int m = 0; m < 4; ++m)
; #pragma unroll
;                     for (int n = 0; n < 2; ++n) acc[a][b][m][n] = (f32x4){0.f, 0.f, 0.f, 0.f};
.LBB0_738:
	s_ashr_i32 s25, s24, 31
	s_lshl_b64 s[0:1], s[24:25], 20
	v_readlane_b32 s26, v255, 9
	v_readlane_b32 s27, v255, 10
	s_add_u32 s26, s26, s0
	s_addc_u32 s27, s27, s1
	s_and_b64 s[0:1], s[38:39], exec
	s_cselect_b32 s25, s27, s23
	s_cselect_b32 s56, s26, s22
	s_ashr_i32 s21, s20, 31
	s_lshl_b64 s[0:1], s[20:21], 20
	s_add_u32 s28, s2, s0
	s_addc_u32 s29, s10, s1
	s_and_b64 s[0:1], s[38:39], exec
	s_cselect_b32 s21, s29, s31
	s_cselect_b32 s57, s28, s30
	s_add_u32 s22, s22, 0x84000
	s_addc_u32 s23, s23, 0
	s_add_u32 s60, s30, 0x8000
	v_mov_b32_e32 v2, 0
	s_addc_u32 s61, s31, 0
	s_mov_b32 s65, -2
	v_mov_b32_e32 v3, v2
	v_mov_b32_e32 v4, v2
	v_mov_b32_e32 v5, v2
	v_mov_b32_e32 v6, v2
	v_mov_b32_e32 v7, v2
	v_mov_b32_e32 v8, v2
	v_mov_b32_e32 v9, v2
	v_mov_b32_e32 v18, v2
	v_mov_b32_e32 v19, v2
	v_mov_b32_e32 v20, v2
	v_mov_b32_e32 v21, v2
	v_mov_b32_e32 v22, v2
	v_mov_b32_e32 v23, v2
	v_mov_b32_e32 v24, v2
	v_mov_b32_e32 v25, v2
	v_mov_b32_e32 v34, v2
	v_mov_b32_e32 v35, v2
	v_mov_b32_e32 v36, v2
	v_mov_b32_e32 v37, v2
	v_mov_b32_e32 v38, v2
	v_mov_b32_e32 v39, v2
	v_mov_b32_e32 v40, v2
	v_mov_b32_e32 v41, v2
	v_mov_b32_e32 v50, v2
	v_mov_b32_e32 v51, v2
	v_mov_b32_e32 v52, v2
	v_mov_b32_e32 v53, v2
	v_mov_b32_e32 v54, v2
	v_mov_b32_e32 v55, v2
	v_mov_b32_e32 v56, v2
	v_mov_b32_e32 v57, v2
	v_mov_b32_e32 v10, v2
	v_mov_b32_e32 v11, v2
	v_mov_b32_e32 v12, v2
	v_mov_b32_e32 v13, v2
	v_mov_b32_e32 v14, v2
	v_mov_b32_e32 v15, v2
	v_mov_b32_e32 v16, v2
	v_mov_b32_e32 v17, v2
	v_mov_b32_e32 v26, v2
	v_mov_b32_e32 v27, v2
	v_mov_b32_e32 v28, v2
	v_mov_b32_e32 v29, v2
	v_mov_b32_e32 v30, v2
	v_mov_b32_e32 v31, v2
	v_mov_b32_e32 v32, v2
	v_mov_b32_e32 v33, v2
	v_mov_b32_e32 v42, v2
	v_mov_b32_e32 v43, v2
	v_mov_b32_e32 v44, v2
	v_mov_b32_e32 v45, v2
	v_mov_b32_e32 v46, v2
	v_mov_b32_e32 v47, v2
	v_mov_b32_e32 v48, v2
	v_mov_b32_e32 v49, v2
	v_mov_b32_e32 v58, v2
	v_mov_b32_e32 v59, v2
	v_mov_b32_e32 v60, v2
	v_mov_b32_e32 v61, v2
	v_mov_b32_e32 v62, v2
	v_mov_b32_e32 v63, v2
	v_mov_b32_e32 v64, v2
	v_mov_b32_e32 v65, v2
	v_mov_b32_e32 v66, v2
	v_mov_b32_e32 v67, v2
	v_mov_b32_e32 v68, v2
	v_mov_b32_e32 v69, v2
	v_mov_b32_e32 v70, v2
	v_mov_b32_e32 v71, v2
	v_mov_b32_e32 v72, v2
	v_mov_b32_e32 v73, v2
	v_mov_b32_e32 v82, v2
	v_mov_b32_e32 v83, v2
	v_mov_b32_e32 v84, v2
	v_mov_b32_e32 v85, v2
	v_mov_b32_e32 v86, v2
	v_mov_b32_e32 v87, v2
	v_mov_b32_e32 v88, v2
	v_mov_b32_e32 v89, v2
	v_mov_b32_e32 v98, v2
	v_mov_b32_e32 v99, v2
	v_mov_b32_e32 v100, v2
	v_mov_b32_e32 v101, v2
	v_mov_b32_e32 v102, v2
	v_mov_b32_e32 v103, v2
	v_mov_b32_e32 v104, v2
	v_mov_b32_e32 v105, v2
	v_mov_b32_e32 v114, v2
	v_mov_b32_e32 v115, v2
	v_mov_b32_e32 v116, v2
	v_mov_b32_e32 v117, v2
	v_mov_b32_e32 v118, v2
	v_mov_b32_e32 v119, v2
	v_mov_b32_e32 v120, v2
	v_mov_b32_e32 v121, v2
	v_mov_b32_e32 v74, v2
	v_mov_b32_e32 v75, v2
	v_mov_b32_e32 v76, v2
	v_mov_b32_e32 v77, v2
	v_mov_b32_e32 v78, v2
	v_mov_b32_e32 v79, v2
	v_mov_b32_e32 v80, v2
	v_mov_b32_e32 v81, v2
	v_mov_b32_e32 v90, v2
	v_mov_b32_e32 v91, v2
	v_mov_b32_e32 v92, v2
	v_mov_b32_e32 v93, v2
	v_mov_b32_e32 v94, v2
	v_mov_b32_e32 v95, v2
	v_mov_b32_e32 v96, v2
	v_mov_b32_e32 v97, v2
	v_mov_b32_e32 v106, v2
	v_mov_b32_e32 v107, v2
	v_mov_b32_e32 v108, v2
	v_mov_b32_e32 v109, v2
	v_mov_b32_e32 v110, v2
	v_mov_b32_e32 v111, v2
	v_mov_b32_e32 v112, v2
	v_mov_b32_e32 v113, v2
	v_mov_b32_e32 v122, v2
	v_mov_b32_e32 v123, v2
	v_mov_b32_e32 v124, v2
	v_mov_b32_e32 v125, v2
	v_mov_b32_e32 v126, v2
	v_mov_b32_e32 v127, v2
	v_mov_b32_e32 v128, v2
	v_mov_b32_e32 v129, v2
	.p2align 6

; __device__ __forceinline__ const char* b_base(const Gemm& g, const Unit& u) { return (const char*)g.Bt + (size_t)u.pn * 2 * (g.K >> 6) * BLK; }
; template <class Epi, bool ALIGN_EPI = true, bool SP2 = true>
; __device__ __forceinline__ void gemm_phase(LAS unsigned char* lds, const Gemm g, const StaticOrder& S, const Epi& E, unsigned long long& tacc, const int tmode) {
;     ...
;         const bool has_next = S.next(ui + 1, nxt);
;         const char* nA = has_next ? a_base(g, nxt) : cA; const char* nB = has_next ? b_base(g, nxt) : cB;
;         unsigned long long tk0 = 0ull; if (tmode == 1) tk0 = __builtin_amdgcn_s_memrealtime(); if (tmode == 3) tk0 = (unsigned long long)clock64();
; #pragma unroll 1
;         for (int t = 0; t < nt; t += 2) {
;             const bool last = (t == nt - 2);
;             const char* a1 = cA + (size_t)(t + 1) * kstepA;
;             const char* a2 = last ? nA : cA + (size_t)(t + 2) * kstepA; const char* b2 = last ? nB : cB + (size_t)(t + 2) * kstepB;
;             const char* a3 = a2 + kstepA; const char* b3 = b2 + kstepB;
.LBB0_1044:
	s_add_u32 s37, s24, 0x8000
	s_addc_u32 vcc_lo, s25, 0
	s_mov_b32 s0, 0
	s_mov_b64 s[42:43], 0x100
	v_mov_b64_e32 v[142:143], v[140:141]
	v_mov_b64_e32 v[144:145], v[138:139]
	.p2align 6

; __device__ __forceinline__ const char* b_base(const Gemm& g, const Unit& u) { return (const char*)g.Bt + (size_t)u.pn * 2 * (g.K >> 6) * BLK; }
; template <class Epi, bool ALIGN_EPI = true, bool SP2 = true>
; __device__ __forceinline__ void gemm_phase(LAS unsigned char* lds, const Gemm g, const StaticOrder& S, const Epi& E, unsigned long long& tacc, const int tmode) {
;     ...
;         const bool has_next = S.next(ui + 1, nxt);
;         const char* nA = has_next ? a_base(g, nxt) : cA; const char* nB = has_next ? b_base(g, nxt) : cB;
;     ...
; #pragma unroll
;         for (int a = 0; a < 2; ++a)
; #pragma unroll
;             for (int b = 0; b < 2; ++b)
; #pragma unroll
;                 for (int m = 0; m < 4; ++m)
; #pragma unroll
;                     for (int n = 0; n < 2; ++n) acc[a][b][m][n] = (f32x4){0.f, 0.f, 0.f, 0.f};
.LBB0_1153:
	s_ashr_i32 s25, s24, 31
	s_lshl_b64 s[0:1], s[24:25], 20
	s_add_u32 s26, s92, s0
	s_addc_u32 s27, s93, s1
	s_and_b64 s[0:1], s[38:39], exec
	s_cselect_b32 s25, s27, s23
	s_cselect_b32 s55, s26, s22
	s_ashr_i32 s21, s20, 31
	s_lshl_b64 s[0:1], s[20:21], 20
	s_add_u32 s28, s2, s0
	s_addc_u32 s29, s42, s1
	s_and_b64 s[0:1], s[38:39], exec
	s_cselect_b32 s21, s29, s31
	s_cselect_b32 s56, s28, s30
	s_add_u32 s22, s22, 0x84000
	s_addc_u32 s23, s23, 0
	s_add_u32 s57, s30, 0x8000
	v_mov_b32_e32 v2, 0
	s_addc_u32 s60, s31, 0
	s_mov_b32 s61, -2
	v_mov_b32_e32 v3, v2
	v_mov_b32_e32 v4, v2
	v_mov_b32_e32 v5, v2
	v_mov_b32_e32 v6, v2
	v_mov_b32_e32 v7, v2
	v_mov_b32_e32 v8, v2
	v_mov_b32_e32 v9, v2
	v_mov_b32_e32 v18, v2
	v_mov_b32_e32 v19, v2
	v_mov_b32_e32 v20, v2
	v_mov_b32_e32 v21, v2
	v_mov_b32_e32 v22, v2
	v_mov_b32_e32 v23, v2
	v_mov_b32_e32 v24, v2
	v_mov_b32_e32 v25, v2
	v_mov_b32_e32 v34, v2
	v_mov_b32_e32 v35, v2
	v_mov_b32_e32 v36, v2
	v_mov_b32_e32 v37, v2
	v_mov_b32_e32 v38, v2
	v_mov_b32_e32 v39, v2
	v_mov_b32_e32 v40, v2
	v_mov_b32_e32 v41, v2
	v_mov_b32_e32 v50, v2
	v_mov_b32_e32 v51, v2
	v_mov_b32_e32 v52, v2
	v_mov_b32_e32 v53, v2
	v_mov_b32_e32 v54, v2
	v_mov_b32_e32 v55, v2
	v_mov_b32_e32 v56, v2
	v_mov_b32_e32 v57, v2
	v_mov_b32_e32 v10, v2
	v_mov_b32_e32 v11, v2
	v_mov_b32_e32 v12, v2
	v_mov_b32_e32 v13, v2
	v_mov_b32_e32 v14, v2
	v_mov_b32_e32 v15, v2
	v_mov_b32_e32 v16, v2
	v_mov_b32_e32 v17, v2
	v_mov_b32_e32 v26, v2
	v_mov_b32_e32 v27, v2
	v_mov_b32_e32 v28, v2
	v_mov_b32_e32 v29, v2
	v_mov_b32_e32 v30, v2
	v_mov_b32_e32 v31, v2
	v_mov_b32_e32 v32, v2
	v_mov_b32_e32 v33, v2
	v_mov_b32_e32 v42, v2
	v_mov_b32_e32 v43, v2
	v_mov_b32_e32 v44, v2
	v_mov_b32_e32 v45, v2
	v_mov_b32_e32 v46, v2
	v_mov_b32_e32 v47, v2
	v_mov_b32_e32 v48, v2
	v_mov_b32_e32 v49, v2
	v_mov_b32_e32 v58, v2
	v_mov_b32_e32 v59, v2
	v_mov_b32_e32 v60, v2
	v_mov_b32_e32 v61, v2
	v_mov_b32_e32 v62, v2
	v_mov_b32_e32 v63, v2
	v_mov_b32_e32 v64, v2
	v_mov_b32_e32 v65, v2
	v_mov_b32_e32 v66, v2
	v_mov_b32_e32 v67, v2
	v_mov_b32_e32 v68, v2
	v_mov_b32_e32 v69, v2
	v_mov_b32_e32 v70, v2
	v_mov_b32_e32 v71, v2
	v_mov_b32_e32 v72, v2
	v_mov_b32_e32 v73, v2
	v_mov_b32_e32 v82, v2
	v_mov_b32_e32 v83, v2
	v_mov_b32_e32 v84, v2
	v_mov_b32_e32 v85, v2
	v_mov_b32_e32 v86, v2
	v_mov_b32_e32 v87, v2
	v_mov_b32_e32 v88, v2
	v_mov_b32_e32 v89, v2
	v_mov_b32_e32 v98, v2
	v_mov_b32_e32 v99, v2
	v_mov_b32_e32 v100, v2
	v_mov_b32_e32 v101, v2
	v_mov_b32_e32 v102, v2
	v_mov_b32_e32 v103, v2
	v_mov_b32_e32 v104, v2
	v_mov_b32_e32 v105, v2
	v_mov_b32_e32 v114, v2
	v_mov_b32_e32 v115, v2
	v_mov_b32_e32 v116, v2
	v_mov_b32_e32 v117, v2
	v_mov_b32_e32 v118, v2
	v_mov_b32_e32 v119, v2
	v_mov_b32_e32 v120, v2
	v_mov_b32_e32 v121, v2
	v_mov_b32_e32 v74, v2
	v_mov_b32_e32 v75, v2
	v_mov_b32_e32 v76, v2
	v_mov_b32_e32 v77, v2
	v_mov_b32_e32 v78, v2
	v_mov_b32_e32 v79, v2
	v_mov_b32_e32 v80, v2
	v_mov_b32_e32 v81, v2
	v_mov_b32_e32 v90, v2
	v_mov_b32_e32 v91, v2
	v_mov_b32_e32 v92, v2
	v_mov_b32_e32 v93, v2
	v_mov_b32_e32 v94, v2
	v_mov_b32_e32 v95, v2
	v_mov_b32_e32 v96, v2
	v_mov_b32_e32 v97, v2
	v_mov_b32_e32 v106, v2
	v_mov_b32_e32 v107, v2
	v_mov_b32_e32 v108, v2
	v_mov_b32_e32 v109, v2
	v_mov_b32_e32 v110, v2
	v_mov_b32_e32 v111, v2
	v_mov_b32_e32 v112, v2
	v_mov_b32_e32 v113, v2
	v_mov_b32_e32 v122, v2
	v_mov_b32_e32 v123, v2
	v_mov_b32_e32 v124, v2
	v_mov_b32_e32 v125, v2
	v_mov_b32_e32 v126, v2
	v_mov_b32_e32 v127, v2
	v_mov_b32_e32 v128, v2
	v_mov_b32_e32 v129, v2
	.p2align 6

; __device__ __forceinline__ const char* b_base(const Gemm& g, const Unit& u) { return (const char*)g.Bt + (size_t)u.pn * 2 * (g.K >> 6) * BLK; }
; template <class Epi, bool ALIGN_EPI = true, bool SP2 = true>
; __device__ __forceinline__ void gemm_phase(LAS unsigned char* lds, const Gemm g, const StaticOrder& S, const Epi& E, unsigned long long& tacc, const int tmode) {
;     ...
;         const bool has_next = S.next(ui + 1, nxt);
;         const char* nA = has_next ? a_base(g, nxt) : cA; const char* nB = has_next ? b_base(g, nxt) : cB;
;         unsigned long long tk0 = 0ull; if (tmode == 1) tk0 = __builtin_amdgcn_s_memrealtime(); if (tmode == 3) tk0 = (unsigned long long)clock64();
; #pragma unroll 1
;         for (int t = 0; t < nt; t += 2) {
;             const bool last = (t == nt - 2);
;             const char* a1 = cA + (size_t)(t + 1) * kstepA;
;             const char* a2 = last ? nA : cA + (size_t)(t + 2) * kstepA; const char* b2 = last ? nB : cB + (size_t)(t + 2) * kstepB;
;             const char* a3 = a2 + kstepA; const char* b3 = b2 + kstepB;
.LBB0_1223:
	s_add_u32 s36, s46, 0x8000
	s_addc_u32 s37, s47, 0
	s_ashr_i32 s27, s26, 31
	s_lshl_b64 s[0:1], s[26:27], 22
	s_add_u32 s28, s52, s0
	s_addc_u32 s29, s53, s1
	s_and_b64 s[0:1], s[40:41], exec
	s_cselect_b32 s27, s29, s23
	s_cselect_b32 vcc_lo, s28, s22
	s_ashr_i32 s25, s24, 31
	s_lshl_b64 s[0:1], s[24:25], 22
	s_add_u32 s30, s2, s0
	s_addc_u32 s31, s54, s1
	s_and_b64 s[0:1], s[40:41], exec
	s_cselect_b32 s25, s31, s47
	s_cselect_b32 vcc_hi, s30, s46
	s_add_u32 s0, s22, 0x204000
	s_addc_u32 s1, s23, 0
	v_lshl_add_u64 v[134:135], s[0:1], 0, v[130:131]
	v_lshl_add_u64 v[136:137], s[0:1], 0, v[132:133]
	s_mov_b32 s81, -2
	s_mov_b64 s[46:47], 0
	.p2align 6

; __device__ __forceinline__ const char* b_base(const Gemm& g, const Unit& u) { return (const char*)g.Bt + (size_t)u.pn * 2 * (g.K >> 6) * BLK; }
; template <class Epi, bool ALIGN_EPI = true, bool SP2 = true>
; __device__ __forceinline__ void gemm_phase(LAS unsigned char* lds, const Gemm g, const StaticOrder& S, const Epi& E, unsigned long long& tacc, const int tmode) {
;     ...
;         const bool has_next = S.next(ui + 1, nxt);
;         const char* nA = has_next ? a_base(g, nxt) : cA; const char* nB = has_next ? b_base(g, nxt) : cB;
;         unsigned long long tk0 = 0ull; if (tmode == 1) tk0 = __builtin_amdgcn_s_memrealtime(); if (tmode == 3) tk0 = (unsigned long long)clock64();
; #pragma unroll 1
;         for (int t = 0; t < nt; t += 2) {
;             const bool last = (t == nt - 2);
;             const char* a1 = cA + (size_t)(t + 1) * kstepA;
;             const char* a2 = last ? nA : cA + (size_t)(t + 2) * kstepA; const char* b2 = last ? nB : cB + (size_t)(t + 2) * kstepB;
;             const char* a3 = a2 + kstepA; const char* b3 = b2 + kstepB;
.LBB0_1284:
	s_add_u32 s86, s40, 0x8000
	s_addc_u32 s87, s41, 0
	s_ashr_i32 s27, s26, 31
	s_lshl_b64 s[0:1], s[26:27], 22
	s_add_u32 s28, s52, s0
	s_addc_u32 s29, s53, s1
	s_and_b64 s[0:1], s[38:39], exec
	s_cselect_b32 s27, s29, s23
	s_cselect_b32 vcc_lo, s28, s22
	s_ashr_i32 s25, s24, 31
	s_lshl_b64 s[0:1], s[24:25], 22
	s_add_u32 s30, s2, s0
	s_addc_u32 s31, s54, s1
	s_and_b64 s[0:1], s[38:39], exec
	s_cselect_b32 s25, s31, s41
	s_cselect_b32 vcc_hi, s30, s40
	s_add_u32 s0, s22, 0x204000
	s_addc_u32 s1, s23, 0
	v_lshl_add_u64 v[128:129], s[0:1], 0, v[130:131]
	v_lshl_add_u64 v[132:133], s[0:1], 0, v[126:127]
	s_mov_b32 s72, -2
	s_mov_b64 s[40:41], 0
	.p2align 6
